# mixers phase: small per-workgroup start offsets ((bid>>3)&3 x 0.3us) to de-phase tile loads within an XCD
# speedup vs baseline: 1.0034x; 1.0034x over previous
; #define LAS __attribute__((address_space(3)))
; #define GAS __attribute__((address_space(1)))
; DI unsigned char* ARGWS(const Ctx& C) { return (unsigned char*)ARGP(C, 22); }
; DI void attn_unit_d32(const Ctx& C, const bf16_t* __restrict__ Z, bf16_t* __restrict__ Y, int b, int qsel, int hsel, bool ctxq, float lam, float post_scale, const float* subln, const float mref) {
;     constexpr int KST = 136, VST = 72, AT_VT = 64 * 136 * 2;
;     const int tid = C.tid, lane = C.lane, w = C.wave, l31 = lane & 31, hh = lane >> 5, sm = w >> 2, qg = w & 3;
;     const int qrow = (ctxq ? NLAT + 256 * b : b * SEQ) + 128 * qsel + 32 * qg + l31;
;     const int qcol = Z_DQ + 128 * hsel + 64 * sm, kcol = Z_DK + 128 * hsel, vcol = Z_DV + 128 * hsel, ycol = 1536 + 128 * hsel;
;     const int nt = ctxq ? 4 : 36;
;     LAS bf16_t* lds16 = (LAS bf16_t*)C.lds;
;     bf16x8 qf[4];
; #pragma unroll
;     for (int ks = 0; ks < 4; ++ks) qf[ks] = *(const GAS bf16x8*)(Z + (size_t)qrow * ZW + qcol + 16 * ks + 8 * hh);
;     const float negm = -mref;
;     f32x16 o[4]; float lsum = 0.f;
; #pragma unroll
;     for (int d = 0; d < 4; ++d)
; #pragma unroll
;         for (int r = 0; r < 16; ++r) o[d][r] = 0.f;
;     u32x4 kA[2], vA[2], kB[2], vB[2];
;     const int krow = tid >> 3, kch = tid & 7, vp2 = 2 * (lane & 31), vhs = lane >> 5;
;     ...
;     const unsigned koff = (unsigned)(krow * ZW + kcol + 8 * kch), voff = (unsigned)(vp2 * ZW + vcol + 8 * (2 * w + vhs));
; DI void phase_mixers(const Ctx& C, int l, bool last) {
;     unsigned char* ws = ARGWS(C);
;     const bf16_t* Z = (const bf16_t*)(ws + WS_Z); bf16_t* Y = (bf16_t*)(ws + WS_Y);
;     const float* misc = (const float*)(ws + WS_MISC);
;     const float lam = misc[l], post = misc[2 + l], mA = misc[8 + 4 * l], mB = misc[9 + 4 * l], mD = misc[10 + 4 * l];
;     const float* sink = ARGP(C, 11) + l * 8; const float* rpb = ARGP(C, 12) + (size_t)l * 8 * 15 * 31; const float* subln = ARGP(C, 16) + l * 128;
;     const bf16_t* cwT = (const bf16_t*)(ws + WS_CWT) + (size_t)l * 4 * 128 * 128; const float* cscale = ARGP(C, 14) + l * 512;
;     const int nC = last ? (NLAT / 64) * 4 : (MROWS / 64) * 4;
;     for (int rep = 0; rep < ((UDUP & 1) ? 2 : 1); ++rep)
;     if (UMASK & 1) for (int u = C.bid; u < 256; u += C.G) { const int b = u >> 6, qb = (u >> 2) & 15, h = u & 3; attn_unit_d32(C, Z, Y, b, qb, h, false, lam, post, subln, mD); }
.LBB0_391:
	s_andn2_b64 vcc, exec, s[0:1]
	s_cbranch_vccnz .LBB0_694
	s_ashr_i32 s85, s84, 31
	v_readlane_b32 s0, v248, 3
	s_cmp_lt_i32 s0, 2
	s_mov_b64 s[0:1], -1
	v_readlane_b32 s81, v249, 63
	v_readlane_b32 s60, v249, 59
	v_readlane_b32 s61, v249, 60
	s_cbranch_scc1 .LBB0_648
	v_readlane_b32 s0, v248, 3
	s_cmp_gt_i32 s0, 2
	s_mov_b64 s[0:1], -1
	s_cbranch_scc0 .LBB0_549
	v_mov_b32_e32 v0, s66
	ds_read_b32 v0, v0
	s_lshl_b32 s0, s84, 7
	s_ashr_i32 s1, s0, 31
	s_mul_i32 s7, s84, 12
	s_mul_hi_i32 s6, s84, 12
	s_waitcnt lgkmcnt(0)
	v_readfirstlane_b32 s30, v0
	v_mov_b32_e32 v0, s96
	ds_read_b32 v0, v0
	s_add_u32 s8, s30, 0x1b800000
	v_ashrrev_i32_e32 v177, 3, v208
	s_movk_i32 s47, 0x100
	s_movk_i32 s41, 0x2000
	s_waitcnt lgkmcnt(0)
	v_readfirstlane_b32 s31, v0
	s_addc_u32 s9, s31, 0
	s_add_u32 s10, s30, 0x17000000
	s_addc_u32 s11, s31, 0
	s_lshl_b64 s[4:5], s[84:85], 2
	s_add_u32 s4, s30, s4
	s_addc_u32 s5, s31, s5
	v_mov_b64_e32 v[2:3], s[4:5]
	s_add_u32 s4, s4, s7
	s_addc_u32 s5, s5, s6
	flat_load_dword v168, v[2:3]
	flat_load_dword v176, v[2:3] offset:8
	v_mov_b64_e32 v[2:3], s[4:5]
	flat_load_dwordx3 v[164:166], v[2:3] offset:32
	v_readlane_b32 s4, v249, 14
	v_readlane_b32 s5, v249, 19
	s_lshl_b64 s[0:1], s[0:1], 2
	v_mov_b32_e32 v0, s4
	ds_read_b32 v0, v0
	v_readlane_b32 s4, v249, 15
	s_mov_b32 s52, 0x3fb8aa3b
	v_readlane_b32 s58, v248, 2
	s_waitcnt lgkmcnt(0)
	v_readfirstlane_b32 s16, v0
	v_mov_b32_e32 v0, s4
	ds_read_b32 v0, v0
	v_readlane_b32 s4, v249, 16
	s_waitcnt lgkmcnt(0)
	v_readfirstlane_b32 s17, v0
	v_mov_b32_e32 v0, s4
	ds_read_b32 v0, v0
	v_readlane_b32 s4, v249, 17
	s_waitcnt lgkmcnt(0)
	v_readfirstlane_b32 s26, v0
	v_mov_b32_e32 v0, s4
	ds_read_b32 v0, v0
	v_readlane_b32 s4, v249, 18
	s_waitcnt lgkmcnt(0)
	v_readfirstlane_b32 s27, v0
	v_mov_b32_e32 v0, s4
	ds_read_b32 v0, v0
	s_waitcnt lgkmcnt(0)
	v_readfirstlane_b32 s4, v0
	v_mov_b32_e32 v0, s5
	ds_read_b32 v0, v0
	s_add_u32 s12, s4, s0
	v_readlane_b32 s0, v249, 20
	s_waitcnt lgkmcnt(0)
	v_readfirstlane_b32 s5, v0
	v_mov_b32_e32 v0, s0
	ds_read_b32 v0, v0
	v_readlane_b32 s0, v249, 21
	s_addc_u32 s13, s5, s1
	s_cmpk_lt_i32 s51, 0x100
	s_cselect_b64 s[4:5], -1, 0
	s_waitcnt lgkmcnt(0)
	v_readfirstlane_b32 s34, v0
	v_mov_b32_e32 v0, s0
	ds_read_b32 v0, v0
	s_movk_i32 s0, 0x1100
	s_cmpk_gt_i32 s51, 0xff
	v_mul_lo_u32 v178, v177, s0
	s_waitcnt lgkmcnt(0)
	v_readfirstlane_b32 s35, v0
	s_waitcnt vmcnt(0)
	v_mov_b32_e32 v169, v168
	v_xor_b32_e32 v4, 0x80000000, v166
	v_mov_b32_e32 v5, v4
	v_mov_b32_e32 v6, v4
	v_mov_b32_e32 v7, v4
	v_mov_b32_e32 v8, v4
	v_mov_b32_e32 v9, v4
	v_mov_b32_e32 v10, v4
	v_mov_b32_e32 v11, v4
	v_mov_b32_e32 v12, v4
	v_mov_b32_e32 v13, v4
	v_mov_b32_e32 v14, v4
	v_mov_b32_e32 v15, v4
	v_mov_b32_e32 v16, v4
	v_mov_b32_e32 v17, v4
	v_mov_b32_e32 v18, v4
	v_mov_b32_e32 v19, v4
	s_cbranch_scc1 .LBB0_412
	v_readlane_b32 s100, v249, 56
	s_nop 3
	s_bfe_u32 s100, s100, 0x20003
	s_cmp_eq_u32 s100, 0
	s_cbranch_scc1 .Lmix_nd
.Lmix_d:
	s_sleep 9
	s_sub_u32 s100, s100, 1
	s_cmp_lg_u32 s100, 0
	s_cbranch_scc1 .Lmix_d
.Lmix_nd:
	v_lshlrev_b32_e32 v21, 3, v206
	v_ashrrev_i32_e32 v20, 5, v206
	v_and_b32_e32 v21, 56, v21
	v_and_b32_e32 v0, 31, v206
	v_lshlrev_b32_e32 v2, 3, v20
	v_or_b32_e32 v22, v178, v21
	v_add_u32_e32 v179, 0xd00, v22
	v_mul_u32_u24_e32 v22, 0x2200, v0
	v_lshl_add_u32 v23, s58, 4, v2
	s_movk_i32 s6, 0xf00
	v_add3_u32 v180, v22, v23, s6
	s_movk_i32 s6, 0x110
	s_ashr_i32 s0, s58, 2
	v_mul_lo_u32 v22, v177, s6
	v_lshlrev_b32_e32 v21, 1, v21
	s_movk_i32 s6, 0x90
	s_lshl_b32 s1, s58, 5
	s_lshl_b32 s18, s0, 6
	v_add3_u32 v181, 0, v22, v21
	v_mul_lo_u32 v21, v23, s6
	s_lshl_b32 s6, s0, 7
	s_and_b32 s1, s1, 0x60
	s_add_i32 s19, s18, 0xb00
	s_add_i32 s6, s6, 0
	v_and_b32_e32 v22, 25, v0
	v_lshrrev_b32_e32 v182, 1, v0
	v_and_b32_e32 v182, 2, v182
	v_or_b32_e32 v22, v22, v182
	v_lshlrev_b32_e32 v182, 1, v0
	v_and_b32_e32 v182, 4, v182
	v_or_b32_e32 v22, v22, v182
	v_lshlrev_b32_e32 v22, 2, v22
	v_lshlrev_b32_e32 v183, 4, v20
	v_or_b32_e32 v187, s1, v0
	s_movk_i32 s1, 0x210
	s_cmp_eq_u32 s0, 1
	v_lshlrev_b32_e32 v166, 2, v20
	v_add3_u32 v182, 0, v21, v22
	v_add_u32_e32 v21, s6, v183
	v_mul_u32_u24_e32 v184, 0x110, v0
	v_add_u32_e32 v22, 0, v2
	v_mul_u32_u24_e32 v185, 0x90, v0
	v_lshlrev_b32_e32 v23, 2, v206
	v_mad_u32_u24 v0, v187, s1, 0
	s_cselect_b64 s[6:7], -1, 0
	s_cmp_lt_u32 s58, 4
	v_ashrrev_i32_e32 v167, 31, v166
	v_ashrrev_i32_e32 v3, 31, v2
	v_xor_b32_e32 v186, 0x80, v23
	s_cselect_b64 s[14:15], -1, 0
	v_lshl_add_u64 v[170:171], v[166:167], 2, s[12:13]
	v_add_u32_e32 v188, v21, v184
	v_add_u32_e32 v189, v183, v185
	v_add_u32_e32 v190, v0, v183
	s_mov_b32 s20, s51
	s_branch .LBB0_397
